# hand-written weight-conversion routine (3-deep prefetch ring) replacing tail-slack conversions, jobs spread over all blocks
# speedup vs baseline: 1.0648x; 1.0175x over previous
.LBB0_87:
	v_readlane_b32 s100, v239, 56
	s_branch .Lcv_entry
.Lcv_ret_gu2:
.LBB0_125:
	s_mov_b64 s[18:19], 0

.Lcv_entry:
	v_writelane_b32 v238, s4, 33
	v_writelane_b32 v238, s5, 34
	v_writelane_b32 v238, s6, 35
	v_writelane_b32 v238, s7, 36
	v_writelane_b32 v238, s8, 37
	v_writelane_b32 v238, s9, 38
	v_writelane_b32 v238, s10, 39
	v_writelane_b32 v238, s11, 40
	v_writelane_b32 v238, s12, 41
	v_writelane_b32 v238, s13, 42
	v_writelane_b32 v238, s14, 43
	v_writelane_b32 v238, s15, 44
	v_writelane_b32 v238, s16, 45
	v_writelane_b32 v238, s17, 46
	v_writelane_b32 v238, s18, 47
	v_writelane_b32 v238, s19, 48
	v_writelane_b32 v238, s20, 49
	v_writelane_b32 v238, s21, 50
	v_writelane_b32 v238, s22, 51
	v_writelane_b32 v238, s23, 52
	v_writelane_b32 v238, s24, 53
	v_writelane_b32 v238, s25, 54
	v_writelane_b32 v238, s26, 55
	v_writelane_b32 v238, s27, 56
	v_writelane_b32 v238, s28, 57
	v_writelane_b32 v238, s29, 58
	v_writelane_b32 v238, s30, 59
	v_writelane_b32 v238, s31, 60
	s_mov_b64 exec, -1
	v_readlane_b32 s4, v242, 1
	v_readlane_b32 s5, v242, 2
	v_readlane_b32 s6, v242, 0
	s_mov_b32 s7, s76
	s_nop 4
	s_load_dwordx2 s[8:9], s[4:5], 0xf8
	s_cmp_lg_u32 s100, 2
	s_cbranch_scc1 .Lcv_np_2
	s_movk_i32 s13, 0x580
	s_movk_i32 s14, 0xb00
	s_movk_i32 s15, 0x160
	s_movk_i32 s16, 0x1080
	s_movk_i32 s17, 0x140
	s_movk_i32 s18, 0x440
	s_movk_i32 s12, 0x3e0
	s_movk_i32 s10, 1
	s_branch .Lcv_plan_done
.Lcv_np_2:
	s_cmp_lg_u32 s100, 13
	s_cbranch_scc1 .Lcv_np_13
	s_movk_i32 s13, 0x580
	s_movk_i32 s14, 0xdc0
	s_movk_i32 s15, 0x160
	s_movk_i32 s16, 0x1240
	s_movk_i32 s17, 0x80
	s_movk_i32 s18, 0x840
	s_movk_i32 s12, 0x4a0
	s_movk_i32 s10, 1
	s_branch .Lcv_plan_done
.Lcv_np_13:
	s_cmp_lg_u32 s100, 10
	s_cbranch_scc1 .Lcv_np_10
	s_movk_i32 s13, 0x580
	s_movk_i32 s14, 0xc60
	s_movk_i32 s15, 0x160
	s_movk_i32 s16, 0x580
	s_movk_i32 s17, 0x2c0
	s_movk_i32 s18, 0x0
	s_movk_i32 s12, 0x420
	s_movk_i32 s10, 1
	s_branch .Lcv_plan_done
.Lcv_np_10:
	s_cmp_lg_u32 s100, 20
	s_cbranch_scc1 .Lcv_np_20
	s_movk_i32 s13, 0x580
	s_movk_i32 s14, 0xf20
	s_movk_i32 s15, 0x160
	s_movk_i32 s16, 0x0
	s_movk_i32 s17, 0x0
	s_movk_i32 s18, 0x0
	s_movk_i32 s12, 0x160
	s_movk_i32 s10, 0
	s_branch .Lcv_plan_done
.Lcv_np_20:
	s_cmp_lg_u32 s100, 5
	s_cbranch_scc1 .Lcv_np_5
	s_movk_i32 s13, 0x3c0
	s_movk_i32 s14, 0x11c0
	s_movk_i32 s15, 0x80
	s_movk_i32 s16, 0x2c0
	s_movk_i32 s17, 0x180
	s_movk_i32 s18, 0x0
	s_movk_i32 s12, 0x200
	s_movk_i32 s10, 0
	s_branch .Lcv_plan_done

.Lcv_plan_done:
.Lcv_mod:
	s_cmp_lt_u32 s13, s7
	s_cbranch_scc1 .Lcv_mod_done
	s_sub_u32 s13, s13, s7
	s_branch .Lcv_mod
.Lcv_mod_done:
	v_lshrrev_b32_e32 v100, 5, v127
	v_and_b32_e32 v101, 31, v127
	v_lshlrev_b32_e32 v101, 4, v101
	v_mul_u32_u24_e32 v96, 0x210, v100
	v_add_u32_e32 v96, v96, v101
	v_and_b32_e32 v98, 0x7f, v127
	v_lshrrev_b32_e32 v99, 7, v127
	v_lshlrev_b32_e32 v102, 6, v99
	v_mul_u32_u24_e32 v97, 0x4200, v99
	v_lshl_add_u32 v97, v98, 2, v97
	s_mov_b32 s19, 0x7060302
	s_sub_u32 s11, s7, s13
	s_cmp_lt_u32 s6, s13
	s_cbranch_scc0 .Lcv_tailblk
	s_cmp_eq_u32 s10, 0
	s_cbranch_scc1 .Lcv_exit
	s_mov_b32 s20, s6
	s_cmp_ge_u32 s20, s12
	s_cbranch_scc1 .Lcv_exit
	s_branch .Lcv_single
.Lcv_tailblk:
	s_sub_u32 s20, s6, s13
	s_mul_i32 s28, s10, s13
	s_add_u32 s20, s20, s28
	s_cmp_ge_u32 s20, s12
	s_cbranch_scc1 .Lcv_exit
	s_waitcnt lgkmcnt(0)
	s_mov_b32 s21, s20
	s_cmp_lt_u32 s21, s12
	s_cselect_b32 s13, s21, s20
	s_cselect_b32 vcc_hi, 1, 0
	s_mov_b32 s28, s13
	s_cmp_lt_u32 s28, s15
	s_cbranch_scc0 .Lcv_m1_1
	s_add_u32 s29, s14, s28
	s_branch .Lcv_m3_1
.Lcv_m1_1:
	s_sub_u32 s28, s28, s15
	s_cmp_lt_u32 s28, s17
	s_cbranch_scc0 .Lcv_m2_1
	s_add_u32 s29, s16, s28
	s_branch .Lcv_m3_1
.Lcv_m2_1:
	s_sub_u32 s28, s28, s17
	s_add_u32 s29, s18, s28
.Lcv_m3_1:
	s_cmpk_lt_u32 s29, 0xb00
	s_cbranch_scc0 .Lcv_dB_2
	s_mul_hi_u32 s28, s29, 0x5d1746
	s_mul_i32 s31, s28, 0x2c0
	s_sub_u32 s31, s29, s31
	s_cmpk_ge_u32 s31, 0x160
	s_cselect_b32 s27, 1, 0
	s_mul_i32 vcc_lo, s27, 0x160
	s_sub_u32 s31, s31, vcc_lo
	s_mul_hi_u32 s25, s31, 0xba2e8bb
	s_mul_i32 vcc_lo, s25, 22
	s_sub_u32 s26, s31, vcc_lo
	s_lshl_b32 s25, s25, 6
	s_lshl_b32 s26, s26, 7
	s_and_b32 s31, s28, 1
	s_mul_i32 s31, s31, 24
	s_lshl_b32 vcc_lo, s27, 3
	s_add_u32 s101, s31, vcc_lo
	s_add_u32 s101, s101, 88
	s_lshr_b32 s98, s28, 1
	s_mul_i32 s98, s98, 0xb00000
	s_movk_i32 s24, 0x2c00
	s_mul_i32 s99, s28, 0xb00000
	s_add_u32 s99, s99, 0x36000
	s_movk_i32 s30, 0x800
	s_add_u32 s27, s27, 1
	s_branch .Lcv_dZ_2
.Lcv_dB_2:
	s_cmpk_lt_u32 s29, 0x1080
	s_cbranch_scc0 .Lcv_dC_2
	s_sub_u32 s31, s29, 0xb00
	s_mul_hi_u32 s28, s31, 0xba2e8c
	s_mul_i32 vcc_lo, s28, 0x160
	s_sub_u32 s31, s31, vcc_lo
	s_lshr_b32 s25, s31, 3
	s_and_b32 s26, s31, 7
	s_lshl_b32 s25, s25, 6
	s_lshl_b32 s26, s26, 7
	s_and_b32 s31, s28, 1
	s_mul_i32 s31, s31, 24
	s_add_u32 s101, s31, 104
	s_lshr_b32 s98, s28, 1
	s_mul_i32 s98, s98, 0xb00000
	s_movk_i32 s24, 0x1000
	s_mul_i32 s99, s28, 0x580000
	s_add_u32 s99, s99, 0x2c36000
	s_movk_i32 s30, 0x1600
	s_mov_b32 s27, 0
	s_branch .Lcv_dZ_2
.Lcv_dC_2:
	s_cmpk_lt_u32 s29, 0x11c0
	s_cbranch_scc0 .Lcv_dD_2
	s_sub_u32 s31, s29, 0x1080
	s_mul_hi_u32 s25, s31, 0xccccccd
	s_mul_i32 vcc_lo, s25, 20
	s_sub_u32 s26, s31, vcc_lo
	s_lshl_b32 s25, s25, 6
	s_lshl_b32 s26, s26, 7
	s_movk_i32 s101, 136
	s_movk_i32 s24, 0x2800
	s_mov_b32 s99, 0x4236000
	s_branch .Lcv_dY_2
.Lcv_dD_2:
	s_cmpk_lt_u32 s29, 0x1240
	s_cbranch_scc0 .Lcv_dE_2
	s_sub_u32 s31, s29, 0x11c0
	s_movk_i32 s101, 224
	s_mov_b32 s99, 0x4736000
	s_branch .Lcv_dX_2
.Lcv_dE_2:
	s_sub_u32 s31, s29, 0x1240
	s_movk_i32 s101, 232
	s_mov_b32 s99, 0x4936000
.Lcv_dX_2:
	s_lshr_b32 s25, s31, 3
	s_and_b32 s26, s31, 7
	s_lshl_b32 s25, s25, 6
	s_lshl_b32 s26, s26, 7
	s_movk_i32 s24, 0x1000
.Lcv_dY_2:
	s_mov_b32 s98, 0
	s_movk_i32 s30, 0x800
	s_mov_b32 s27, 0
.Lcv_dZ_2:
	s_load_dwordx2 s[22:23], s[4:5], s101
	s_mul_i32 s24, s24, vcc_hi
	s_mul_i32 s31, s25, s24
	s_lshl_b32 s28, s26, 2
	s_add_u32 s31, s31, s28
	s_add_u32 s31, s31, s98
	s_lshl_b32 s28, s24, 3
	v_mad_u32_u24 v104, v100, s24, v101
	v_add_u32_e32 v105, s28, v104
	v_add_u32_e32 v106, s28, v105
	v_add_u32_e32 v107, s28, v106
	v_add_u32_e32 v108, s28, v107
	v_add_u32_e32 v109, s28, v108
	v_add_u32_e32 v110, s28, v109
	v_add_u32_e32 v111, s28, v110
	s_waitcnt lgkmcnt(0)
	s_add_u32 s22, s22, s31
	s_addc_u32 s23, s23, 0
	global_load_dwordx4 v[0:3], v104, s[22:23] nt
	global_load_dwordx4 v[4:7], v105, s[22:23] nt
	global_load_dwordx4 v[8:11], v106, s[22:23] nt
	global_load_dwordx4 v[12:15], v107, s[22:23] nt
	global_load_dwordx4 v[16:19], v108, s[22:23] nt
	global_load_dwordx4 v[20:23], v109, s[22:23] nt
	global_load_dwordx4 v[24:27], v110, s[22:23] nt
	global_load_dwordx4 v[28:31], v111, s[22:23] nt
	s_add_u32 s21, s21, s11
	s_cmp_lt_u32 s21, s12
	s_cselect_b32 s13, s21, s20
	s_cselect_b32 vcc_hi, 1, 0
	s_mov_b32 s28, s13
	s_cmp_lt_u32 s28, s15
	s_cbranch_scc0 .Lcv_m1_3
	s_add_u32 s29, s14, s28
	s_branch .Lcv_m3_3

.Lcv_dZ_4:
	s_load_dwordx2 s[22:23], s[4:5], s101
	s_mul_i32 s24, s24, vcc_hi
	s_mul_i32 s31, s25, s24
	s_lshl_b32 s28, s26, 2
	s_add_u32 s31, s31, s28
	s_add_u32 s31, s31, s98
	s_lshl_b32 s28, s24, 3
	v_mad_u32_u24 v104, v100, s24, v101
	v_add_u32_e32 v105, s28, v104
	v_add_u32_e32 v106, s28, v105
	v_add_u32_e32 v107, s28, v106
	v_add_u32_e32 v108, s28, v107
	v_add_u32_e32 v109, s28, v108
	v_add_u32_e32 v110, s28, v109
	v_add_u32_e32 v111, s28, v110
	s_waitcnt lgkmcnt(0)
	s_add_u32 s22, s22, s31
	s_addc_u32 s23, s23, 0
	global_load_dwordx4 v[32:35], v104, s[22:23] nt
	global_load_dwordx4 v[36:39], v105, s[22:23] nt
	global_load_dwordx4 v[40:43], v106, s[22:23] nt
	global_load_dwordx4 v[44:47], v107, s[22:23] nt
	global_load_dwordx4 v[48:51], v108, s[22:23] nt
	global_load_dwordx4 v[52:55], v109, s[22:23] nt
	global_load_dwordx4 v[56:59], v110, s[22:23] nt
	global_load_dwordx4 v[60:63], v111, s[22:23] nt
	s_add_u32 s21, s21, s11
	s_cmp_lt_u32 s21, s12
	s_cselect_b32 s13, s21, s20
	s_cselect_b32 vcc_hi, 1, 0
	s_mov_b32 s28, s13
	s_cmp_lt_u32 s28, s15
	s_cbranch_scc0 .Lcv_m1_5
	s_add_u32 s29, s14, s28
	s_branch .Lcv_m3_5

.Lcv_dZ_6:
	s_load_dwordx2 s[22:23], s[4:5], s101
	s_mul_i32 s24, s24, vcc_hi
	s_mul_i32 s31, s25, s24
	s_lshl_b32 s28, s26, 2
	s_add_u32 s31, s31, s28
	s_add_u32 s31, s31, s98
	s_lshl_b32 s28, s24, 3
	v_mad_u32_u24 v104, v100, s24, v101
	v_add_u32_e32 v105, s28, v104
	v_add_u32_e32 v106, s28, v105
	v_add_u32_e32 v107, s28, v106
	v_add_u32_e32 v108, s28, v107
	v_add_u32_e32 v109, s28, v108
	v_add_u32_e32 v110, s28, v109
	v_add_u32_e32 v111, s28, v110
	s_waitcnt lgkmcnt(0)
	s_add_u32 s22, s22, s31
	s_addc_u32 s23, s23, 0
	global_load_dwordx4 v[64:67], v104, s[22:23] nt
	global_load_dwordx4 v[68:71], v105, s[22:23] nt
	global_load_dwordx4 v[72:75], v106, s[22:23] nt
	global_load_dwordx4 v[76:79], v107, s[22:23] nt
	global_load_dwordx4 v[80:83], v108, s[22:23] nt
	global_load_dwordx4 v[84:87], v109, s[22:23] nt
	global_load_dwordx4 v[88:91], v110, s[22:23] nt
	global_load_dwordx4 v[92:95], v111, s[22:23] nt
	s_add_u32 s21, s21, s11
	s_cmp_ge_u32 s20, s12
	s_cbranch_scc1 .Lcv_done
	s_waitcnt vmcnt(16)
	ds_write_b128 v96, v[0:3] offset:0
	ds_write_b128 v96, v[4:7] offset:4224
	ds_write_b128 v96, v[8:11] offset:8448
	ds_write_b128 v96, v[12:15] offset:12672
	ds_write_b128 v96, v[16:19] offset:16896
	ds_write_b128 v96, v[20:23] offset:21120
	ds_write_b128 v96, v[24:27] offset:25344
	ds_write_b128 v96, v[28:31] offset:29568
	s_waitcnt lgkmcnt(0)
	s_barrier
	s_cmp_lt_u32 s21, s12
	s_cselect_b32 s13, s21, s20
	s_cselect_b32 vcc_hi, 1, 0
	s_mov_b32 s28, s13
	s_cmp_lt_u32 s28, s15
	s_cbranch_scc0 .Lcv_m1_8
	s_add_u32 s29, s14, s28
	s_branch .Lcv_m3_8

.Lcv_dZ_9:
	s_load_dwordx2 s[22:23], s[4:5], s101
	s_mul_i32 s24, s24, vcc_hi
	s_mul_i32 s31, s25, s24
	s_lshl_b32 s28, s26, 2
	s_add_u32 s31, s31, s28
	s_add_u32 s31, s31, s98
	s_lshl_b32 s28, s24, 3
	v_mad_u32_u24 v104, v100, s24, v101
	v_add_u32_e32 v105, s28, v104
	v_add_u32_e32 v106, s28, v105
	v_add_u32_e32 v107, s28, v106
	v_add_u32_e32 v108, s28, v107
	v_add_u32_e32 v109, s28, v108
	v_add_u32_e32 v110, s28, v109
	v_add_u32_e32 v111, s28, v110
	s_waitcnt lgkmcnt(0)
	s_add_u32 s22, s22, s31
	s_addc_u32 s23, s23, 0
	global_load_dwordx4 v[0:3], v104, s[22:23] nt
	global_load_dwordx4 v[4:7], v105, s[22:23] nt
	global_load_dwordx4 v[8:11], v106, s[22:23] nt
	global_load_dwordx4 v[12:15], v107, s[22:23] nt
	global_load_dwordx4 v[16:19], v108, s[22:23] nt
	global_load_dwordx4 v[20:23], v109, s[22:23] nt
	global_load_dwordx4 v[24:27], v110, s[22:23] nt
	global_load_dwordx4 v[28:31], v111, s[22:23] nt
	s_mov_b32 s28, s20
	s_cmp_lt_u32 s28, s15
	s_cbranch_scc0 .Lcv_m1_10
	s_add_u32 s29, s14, s28
	s_branch .Lcv_m3_10

.Lcv_dZ_11:
	s_lshl_b32 s28, s25, 1
	s_add_u32 s28, s28, s99
	s_add_u32 s22, s8, s28
	s_addc_u32 s23, s9, 0
	v_add_u32_e32 v113, s26, v98
	s_cmp_eq_u32 s27, 0
	s_cbranch_scc1 .Lcv_plain_7
	s_lshl_b32 s28, s27, 5
	s_add_u32 s28, s28, 0xffffffe0
	v_lshrrev_b32_e32 v115, 5, v113
	v_and_b32_e32 v113, 31, v113
	v_lshl_add_u32 v113, v115, 6, v113
	v_add_u32_e32 v113, s28, v113
.Lcv_plain_7:
	v_mul_lo_u32 v112, v113, s30
	v_add_u32_e32 v112, v112, v102
	ds_read_b32 v182, v97 offset:0
	ds_read_b32 v183, v97 offset:528
	ds_read_b32 v184, v97 offset:1056
	ds_read_b32 v185, v97 offset:1584
	ds_read_b32 v186, v97 offset:2112
	ds_read_b32 v187, v97 offset:2640
	ds_read_b32 v188, v97 offset:3168
	ds_read_b32 v189, v97 offset:3696
	ds_read_b32 v190, v97 offset:4224
	ds_read_b32 v191, v97 offset:4752
	ds_read_b32 v192, v97 offset:5280
	ds_read_b32 v193, v97 offset:5808
	ds_read_b32 v194, v97 offset:6336
	ds_read_b32 v195, v97 offset:6864
	ds_read_b32 v196, v97 offset:7392
	ds_read_b32 v197, v97 offset:7920
	ds_read_b32 v198, v97 offset:8448
	ds_read_b32 v199, v97 offset:8976
	ds_read_b32 v200, v97 offset:9504
	ds_read_b32 v201, v97 offset:10032
	ds_read_b32 v202, v97 offset:10560
	ds_read_b32 v203, v97 offset:11088
	ds_read_b32 v204, v97 offset:11616
	ds_read_b32 v205, v97 offset:12144
	ds_read_b32 v206, v97 offset:12672
	ds_read_b32 v207, v97 offset:13200
	ds_read_b32 v208, v97 offset:13728
	ds_read_b32 v209, v97 offset:14256
	ds_read_b32 v210, v97 offset:14784
	ds_read_b32 v211, v97 offset:15312
	ds_read_b32 v212, v97 offset:15840
	ds_read_b32 v213, v97 offset:16368
	s_waitcnt lgkmcnt(15)
	v_bfe_u32 v115, v182, 16, 1
	v_bfe_u32 v116, v183, 16, 1
	v_add3_u32 v182, v182, v115, s33
	v_add3_u32 v183, v183, v116, s33
	v_perm_b32 v216, v183, v182, s19
	v_bfe_u32 v115, v184, 16, 1
	v_bfe_u32 v116, v185, 16, 1
	v_add3_u32 v184, v184, v115, s33
	v_add3_u32 v185, v185, v116, s33
	v_perm_b32 v217, v185, v184, s19
	v_bfe_u32 v115, v186, 16, 1
	v_bfe_u32 v116, v187, 16, 1
	v_add3_u32 v186, v186, v115, s33
	v_add3_u32 v187, v187, v116, s33
	v_perm_b32 v218, v187, v186, s19
	v_bfe_u32 v115, v188, 16, 1
	v_bfe_u32 v116, v189, 16, 1
	v_add3_u32 v188, v188, v115, s33
	v_add3_u32 v189, v189, v116, s33
	v_perm_b32 v219, v189, v188, s19
	v_bfe_u32 v115, v190, 16, 1
	v_bfe_u32 v116, v191, 16, 1
	v_add3_u32 v190, v190, v115, s33
	v_add3_u32 v191, v191, v116, s33
	v_perm_b32 v220, v191, v190, s19
	v_bfe_u32 v115, v192, 16, 1
	v_bfe_u32 v116, v193, 16, 1
	v_add3_u32 v192, v192, v115, s33
	v_add3_u32 v193, v193, v116, s33
	v_perm_b32 v221, v193, v192, s19
	v_bfe_u32 v115, v194, 16, 1
	v_bfe_u32 v116, v195, 16, 1
	v_add3_u32 v194, v194, v115, s33
	v_add3_u32 v195, v195, v116, s33
	v_perm_b32 v222, v195, v194, s19
	v_bfe_u32 v115, v196, 16, 1
	v_bfe_u32 v116, v197, 16, 1
	v_add3_u32 v196, v196, v115, s33
	v_add3_u32 v197, v197, v116, s33
	v_perm_b32 v223, v197, v196, s19
	s_waitcnt lgkmcnt(8)
	v_bfe_u32 v115, v198, 16, 1
	v_bfe_u32 v116, v199, 16, 1
	v_add3_u32 v198, v198, v115, s33
	v_add3_u32 v199, v199, v116, s33
	v_perm_b32 v224, v199, v198, s19
	v_bfe_u32 v115, v200, 16, 1
	v_bfe_u32 v116, v201, 16, 1
	v_add3_u32 v200, v200, v115, s33
	v_add3_u32 v201, v201, v116, s33
	v_perm_b32 v225, v201, v200, s19
	v_bfe_u32 v115, v202, 16, 1
	v_bfe_u32 v116, v203, 16, 1
	v_add3_u32 v202, v202, v115, s33
	v_add3_u32 v203, v203, v116, s33
	v_perm_b32 v226, v203, v202, s19
	v_bfe_u32 v115, v204, 16, 1
	v_bfe_u32 v116, v205, 16, 1
	v_add3_u32 v204, v204, v115, s33
	v_add3_u32 v205, v205, v116, s33
	v_perm_b32 v227, v205, v204, s19
	s_waitcnt lgkmcnt(0)
	v_bfe_u32 v115, v206, 16, 1
	v_bfe_u32 v116, v207, 16, 1
	v_add3_u32 v206, v206, v115, s33
	v_add3_u32 v207, v207, v116, s33
	v_perm_b32 v228, v207, v206, s19
	v_bfe_u32 v115, v208, 16, 1
	v_bfe_u32 v116, v209, 16, 1
	v_add3_u32 v208, v208, v115, s33
	v_add3_u32 v209, v209, v116, s33
	v_perm_b32 v229, v209, v208, s19
	v_bfe_u32 v115, v210, 16, 1
	v_bfe_u32 v116, v211, 16, 1
	v_add3_u32 v210, v210, v115, s33
	v_add3_u32 v211, v211, v116, s33
	v_perm_b32 v230, v211, v210, s19
	v_bfe_u32 v115, v212, 16, 1
	v_bfe_u32 v116, v213, 16, 1
	v_add3_u32 v212, v212, v115, s33
	v_add3_u32 v213, v213, v116, s33
	v_perm_b32 v231, v213, v212, s19
	global_store_dwordx4 v112, v[216:219], s[22:23] offset:0
	global_store_dwordx4 v112, v[220:223], s[22:23] offset:16
	global_store_dwordx4 v112, v[224:227], s[22:23] offset:32
	global_store_dwordx4 v112, v[228:231], s[22:23] offset:48
	s_barrier
	s_add_u32 s20, s20, s11
	s_add_u32 s21, s21, s11
	s_cmp_ge_u32 s20, s12
	s_cbranch_scc1 .Lcv_done
	s_waitcnt vmcnt(20)
	ds_write_b128 v96, v[32:35] offset:0
	ds_write_b128 v96, v[36:39] offset:4224
	ds_write_b128 v96, v[40:43] offset:8448
	ds_write_b128 v96, v[44:47] offset:12672
	ds_write_b128 v96, v[48:51] offset:16896
	ds_write_b128 v96, v[52:55] offset:21120
	ds_write_b128 v96, v[56:59] offset:25344
	ds_write_b128 v96, v[60:63] offset:29568
	s_waitcnt lgkmcnt(0)
	s_barrier
	s_cmp_lt_u32 s21, s12
	s_cselect_b32 s13, s21, s20
	s_cselect_b32 vcc_hi, 1, 0
	s_mov_b32 s28, s13
	s_cmp_lt_u32 s28, s15
	s_cbranch_scc0 .Lcv_m1_13
	s_add_u32 s29, s14, s28
	s_branch .Lcv_m3_13

.Lcv_dZ_14:
	s_load_dwordx2 s[22:23], s[4:5], s101
	s_mul_i32 s24, s24, vcc_hi
	s_mul_i32 s31, s25, s24
	s_lshl_b32 s28, s26, 2
	s_add_u32 s31, s31, s28
	s_add_u32 s31, s31, s98
	s_lshl_b32 s28, s24, 3
	v_mad_u32_u24 v104, v100, s24, v101
	v_add_u32_e32 v105, s28, v104
	v_add_u32_e32 v106, s28, v105
	v_add_u32_e32 v107, s28, v106
	v_add_u32_e32 v108, s28, v107
	v_add_u32_e32 v109, s28, v108
	v_add_u32_e32 v110, s28, v109
	v_add_u32_e32 v111, s28, v110
	s_waitcnt lgkmcnt(0)
	s_add_u32 s22, s22, s31
	s_addc_u32 s23, s23, 0
	global_load_dwordx4 v[32:35], v104, s[22:23] nt
	global_load_dwordx4 v[36:39], v105, s[22:23] nt
	global_load_dwordx4 v[40:43], v106, s[22:23] nt
	global_load_dwordx4 v[44:47], v107, s[22:23] nt
	global_load_dwordx4 v[48:51], v108, s[22:23] nt
	global_load_dwordx4 v[52:55], v109, s[22:23] nt
	global_load_dwordx4 v[56:59], v110, s[22:23] nt
	global_load_dwordx4 v[60:63], v111, s[22:23] nt
	s_mov_b32 s28, s20
	s_cmp_lt_u32 s28, s15
	s_cbranch_scc0 .Lcv_m1_15
	s_add_u32 s29, s14, s28
	s_branch .Lcv_m3_15

.Lcv_plain_12:
	v_mul_lo_u32 v112, v113, s30
	v_add_u32_e32 v112, v112, v102
	ds_read_b32 v182, v97 offset:0
	ds_read_b32 v183, v97 offset:528
	ds_read_b32 v184, v97 offset:1056
	ds_read_b32 v185, v97 offset:1584
	ds_read_b32 v186, v97 offset:2112
	ds_read_b32 v187, v97 offset:2640
	ds_read_b32 v188, v97 offset:3168
	ds_read_b32 v189, v97 offset:3696
	ds_read_b32 v190, v97 offset:4224
	ds_read_b32 v191, v97 offset:4752
	ds_read_b32 v192, v97 offset:5280
	ds_read_b32 v193, v97 offset:5808
	ds_read_b32 v194, v97 offset:6336
	ds_read_b32 v195, v97 offset:6864
	ds_read_b32 v196, v97 offset:7392
	ds_read_b32 v197, v97 offset:7920
	ds_read_b32 v198, v97 offset:8448
	ds_read_b32 v199, v97 offset:8976
	ds_read_b32 v200, v97 offset:9504
	ds_read_b32 v201, v97 offset:10032
	ds_read_b32 v202, v97 offset:10560
	ds_read_b32 v203, v97 offset:11088
	ds_read_b32 v204, v97 offset:11616
	ds_read_b32 v205, v97 offset:12144
	ds_read_b32 v206, v97 offset:12672
	ds_read_b32 v207, v97 offset:13200
	ds_read_b32 v208, v97 offset:13728
	ds_read_b32 v209, v97 offset:14256
	ds_read_b32 v210, v97 offset:14784
	ds_read_b32 v211, v97 offset:15312
	ds_read_b32 v212, v97 offset:15840
	ds_read_b32 v213, v97 offset:16368
	s_waitcnt lgkmcnt(15)
	v_bfe_u32 v115, v182, 16, 1
	v_bfe_u32 v116, v183, 16, 1
	v_add3_u32 v182, v182, v115, s33
	v_add3_u32 v183, v183, v116, s33
	v_perm_b32 v216, v183, v182, s19
	v_bfe_u32 v115, v184, 16, 1
	v_bfe_u32 v116, v185, 16, 1
	v_add3_u32 v184, v184, v115, s33
	v_add3_u32 v185, v185, v116, s33
	v_perm_b32 v217, v185, v184, s19
	v_bfe_u32 v115, v186, 16, 1
	v_bfe_u32 v116, v187, 16, 1
	v_add3_u32 v186, v186, v115, s33
	v_add3_u32 v187, v187, v116, s33
	v_perm_b32 v218, v187, v186, s19
	v_bfe_u32 v115, v188, 16, 1
	v_bfe_u32 v116, v189, 16, 1
	v_add3_u32 v188, v188, v115, s33
	v_add3_u32 v189, v189, v116, s33
	v_perm_b32 v219, v189, v188, s19
	v_bfe_u32 v115, v190, 16, 1
	v_bfe_u32 v116, v191, 16, 1
	v_add3_u32 v190, v190, v115, s33
	v_add3_u32 v191, v191, v116, s33
	v_perm_b32 v220, v191, v190, s19
	v_bfe_u32 v115, v192, 16, 1
	v_bfe_u32 v116, v193, 16, 1
	v_add3_u32 v192, v192, v115, s33
	v_add3_u32 v193, v193, v116, s33
	v_perm_b32 v221, v193, v192, s19
	v_bfe_u32 v115, v194, 16, 1
	v_bfe_u32 v116, v195, 16, 1
	v_add3_u32 v194, v194, v115, s33
	v_add3_u32 v195, v195, v116, s33
	v_perm_b32 v222, v195, v194, s19
	v_bfe_u32 v115, v196, 16, 1
	v_bfe_u32 v116, v197, 16, 1
	v_add3_u32 v196, v196, v115, s33
	v_add3_u32 v197, v197, v116, s33
	v_perm_b32 v223, v197, v196, s19
	s_waitcnt lgkmcnt(8)
	v_bfe_u32 v115, v198, 16, 1
	v_bfe_u32 v116, v199, 16, 1
	v_add3_u32 v198, v198, v115, s33
	v_add3_u32 v199, v199, v116, s33
	v_perm_b32 v224, v199, v198, s19
	v_bfe_u32 v115, v200, 16, 1
	v_bfe_u32 v116, v201, 16, 1
	v_add3_u32 v200, v200, v115, s33
	v_add3_u32 v201, v201, v116, s33
	v_perm_b32 v225, v201, v200, s19
	v_bfe_u32 v115, v202, 16, 1
	v_bfe_u32 v116, v203, 16, 1
	v_add3_u32 v202, v202, v115, s33
	v_add3_u32 v203, v203, v116, s33
	v_perm_b32 v226, v203, v202, s19
	v_bfe_u32 v115, v204, 16, 1
	v_bfe_u32 v116, v205, 16, 1
	v_add3_u32 v204, v204, v115, s33
	v_add3_u32 v205, v205, v116, s33
	v_perm_b32 v227, v205, v204, s19
	s_waitcnt lgkmcnt(0)
	v_bfe_u32 v115, v206, 16, 1
	v_bfe_u32 v116, v207, 16, 1
	v_add3_u32 v206, v206, v115, s33
	v_add3_u32 v207, v207, v116, s33
	v_perm_b32 v228, v207, v206, s19
	v_bfe_u32 v115, v208, 16, 1
	v_bfe_u32 v116, v209, 16, 1
	v_add3_u32 v208, v208, v115, s33
	v_add3_u32 v209, v209, v116, s33
	v_perm_b32 v229, v209, v208, s19
	v_bfe_u32 v115, v210, 16, 1
	v_bfe_u32 v116, v211, 16, 1
	v_add3_u32 v210, v210, v115, s33
	v_add3_u32 v211, v211, v116, s33
	v_perm_b32 v230, v211, v210, s19
	v_bfe_u32 v115, v212, 16, 1
	v_bfe_u32 v116, v213, 16, 1
	v_add3_u32 v212, v212, v115, s33
	v_add3_u32 v213, v213, v116, s33
	v_perm_b32 v231, v213, v212, s19
	global_store_dwordx4 v112, v[216:219], s[22:23] offset:0
	global_store_dwordx4 v112, v[220:223], s[22:23] offset:16
	global_store_dwordx4 v112, v[224:227], s[22:23] offset:32
	global_store_dwordx4 v112, v[228:231], s[22:23] offset:48
	s_barrier
	s_add_u32 s20, s20, s11
	s_add_u32 s21, s21, s11
	s_cmp_ge_u32 s20, s12
	s_cbranch_scc1 .Lcv_done
	s_waitcnt vmcnt(24)
	ds_write_b128 v96, v[64:67] offset:0
	ds_write_b128 v96, v[68:71] offset:4224
	ds_write_b128 v96, v[72:75] offset:8448
	ds_write_b128 v96, v[76:79] offset:12672
	ds_write_b128 v96, v[80:83] offset:16896
	ds_write_b128 v96, v[84:87] offset:21120
	ds_write_b128 v96, v[88:91] offset:25344
	ds_write_b128 v96, v[92:95] offset:29568
	s_waitcnt lgkmcnt(0)
	s_barrier
	s_cmp_lt_u32 s21, s12
	s_cselect_b32 s13, s21, s20
	s_cselect_b32 vcc_hi, 1, 0
	s_mov_b32 s28, s13
	s_cmp_lt_u32 s28, s15
	s_cbranch_scc0 .Lcv_m1_18
	s_add_u32 s29, s14, s28
	s_branch .Lcv_m3_18

.Lcv_dZ_19:
	s_load_dwordx2 s[22:23], s[4:5], s101
	s_mul_i32 s24, s24, vcc_hi
	s_mul_i32 s31, s25, s24
	s_lshl_b32 s28, s26, 2
	s_add_u32 s31, s31, s28
	s_add_u32 s31, s31, s98
	s_lshl_b32 s28, s24, 3
	v_mad_u32_u24 v104, v100, s24, v101
	v_add_u32_e32 v105, s28, v104
	v_add_u32_e32 v106, s28, v105
	v_add_u32_e32 v107, s28, v106
	v_add_u32_e32 v108, s28, v107
	v_add_u32_e32 v109, s28, v108
	v_add_u32_e32 v110, s28, v109
	v_add_u32_e32 v111, s28, v110
	s_waitcnt lgkmcnt(0)
	s_add_u32 s22, s22, s31
	s_addc_u32 s23, s23, 0
	global_load_dwordx4 v[64:67], v104, s[22:23] nt
	global_load_dwordx4 v[68:71], v105, s[22:23] nt
	global_load_dwordx4 v[72:75], v106, s[22:23] nt
	global_load_dwordx4 v[76:79], v107, s[22:23] nt
	global_load_dwordx4 v[80:83], v108, s[22:23] nt
	global_load_dwordx4 v[84:87], v109, s[22:23] nt
	global_load_dwordx4 v[88:91], v110, s[22:23] nt
	global_load_dwordx4 v[92:95], v111, s[22:23] nt
	s_mov_b32 s28, s20
	s_cmp_lt_u32 s28, s15
	s_cbranch_scc0 .Lcv_m1_20
	s_add_u32 s29, s14, s28
	s_branch .Lcv_m3_20

.Lcv_plain_17:
	v_mul_lo_u32 v112, v113, s30
	v_add_u32_e32 v112, v112, v102
	ds_read_b32 v182, v97 offset:0
	ds_read_b32 v183, v97 offset:528
	ds_read_b32 v184, v97 offset:1056
	ds_read_b32 v185, v97 offset:1584
	ds_read_b32 v186, v97 offset:2112
	ds_read_b32 v187, v97 offset:2640
	ds_read_b32 v188, v97 offset:3168
	ds_read_b32 v189, v97 offset:3696
	ds_read_b32 v190, v97 offset:4224
	ds_read_b32 v191, v97 offset:4752
	ds_read_b32 v192, v97 offset:5280
	ds_read_b32 v193, v97 offset:5808
	ds_read_b32 v194, v97 offset:6336
	ds_read_b32 v195, v97 offset:6864
	ds_read_b32 v196, v97 offset:7392
	ds_read_b32 v197, v97 offset:7920
	ds_read_b32 v198, v97 offset:8448
	ds_read_b32 v199, v97 offset:8976
	ds_read_b32 v200, v97 offset:9504
	ds_read_b32 v201, v97 offset:10032
	ds_read_b32 v202, v97 offset:10560
	ds_read_b32 v203, v97 offset:11088
	ds_read_b32 v204, v97 offset:11616
	ds_read_b32 v205, v97 offset:12144
	ds_read_b32 v206, v97 offset:12672
	ds_read_b32 v207, v97 offset:13200
	ds_read_b32 v208, v97 offset:13728
	ds_read_b32 v209, v97 offset:14256
	ds_read_b32 v210, v97 offset:14784
	ds_read_b32 v211, v97 offset:15312
	ds_read_b32 v212, v97 offset:15840
	ds_read_b32 v213, v97 offset:16368
	s_waitcnt lgkmcnt(15)
	v_bfe_u32 v115, v182, 16, 1
	v_bfe_u32 v116, v183, 16, 1
	v_add3_u32 v182, v182, v115, s33
	v_add3_u32 v183, v183, v116, s33
	v_perm_b32 v216, v183, v182, s19
	v_bfe_u32 v115, v184, 16, 1
	v_bfe_u32 v116, v185, 16, 1
	v_add3_u32 v184, v184, v115, s33
	v_add3_u32 v185, v185, v116, s33
	v_perm_b32 v217, v185, v184, s19
	v_bfe_u32 v115, v186, 16, 1
	v_bfe_u32 v116, v187, 16, 1
	v_add3_u32 v186, v186, v115, s33
	v_add3_u32 v187, v187, v116, s33
	v_perm_b32 v218, v187, v186, s19
	v_bfe_u32 v115, v188, 16, 1
	v_bfe_u32 v116, v189, 16, 1
	v_add3_u32 v188, v188, v115, s33
	v_add3_u32 v189, v189, v116, s33
	v_perm_b32 v219, v189, v188, s19
	v_bfe_u32 v115, v190, 16, 1
	v_bfe_u32 v116, v191, 16, 1
	v_add3_u32 v190, v190, v115, s33
	v_add3_u32 v191, v191, v116, s33
	v_perm_b32 v220, v191, v190, s19
	v_bfe_u32 v115, v192, 16, 1
	v_bfe_u32 v116, v193, 16, 1
	v_add3_u32 v192, v192, v115, s33
	v_add3_u32 v193, v193, v116, s33
	v_perm_b32 v221, v193, v192, s19
	v_bfe_u32 v115, v194, 16, 1
	v_bfe_u32 v116, v195, 16, 1
	v_add3_u32 v194, v194, v115, s33
	v_add3_u32 v195, v195, v116, s33
	v_perm_b32 v222, v195, v194, s19
	v_bfe_u32 v115, v196, 16, 1
	v_bfe_u32 v116, v197, 16, 1
	v_add3_u32 v196, v196, v115, s33
	v_add3_u32 v197, v197, v116, s33
	v_perm_b32 v223, v197, v196, s19
	s_waitcnt lgkmcnt(8)
	v_bfe_u32 v115, v198, 16, 1
	v_bfe_u32 v116, v199, 16, 1
	v_add3_u32 v198, v198, v115, s33
	v_add3_u32 v199, v199, v116, s33
	v_perm_b32 v224, v199, v198, s19
	v_bfe_u32 v115, v200, 16, 1
	v_bfe_u32 v116, v201, 16, 1
	v_add3_u32 v200, v200, v115, s33
	v_add3_u32 v201, v201, v116, s33
	v_perm_b32 v225, v201, v200, s19
	v_bfe_u32 v115, v202, 16, 1
	v_bfe_u32 v116, v203, 16, 1
	v_add3_u32 v202, v202, v115, s33
	v_add3_u32 v203, v203, v116, s33
	v_perm_b32 v226, v203, v202, s19
	v_bfe_u32 v115, v204, 16, 1
	v_bfe_u32 v116, v205, 16, 1
	v_add3_u32 v204, v204, v115, s33
	v_add3_u32 v205, v205, v116, s33
	v_perm_b32 v227, v205, v204, s19
	s_waitcnt lgkmcnt(0)
	v_bfe_u32 v115, v206, 16, 1
	v_bfe_u32 v116, v207, 16, 1
	v_add3_u32 v206, v206, v115, s33
	v_add3_u32 v207, v207, v116, s33
	v_perm_b32 v228, v207, v206, s19
	v_bfe_u32 v115, v208, 16, 1
	v_bfe_u32 v116, v209, 16, 1
	v_add3_u32 v208, v208, v115, s33
	v_add3_u32 v209, v209, v116, s33
	v_perm_b32 v229, v209, v208, s19
	v_bfe_u32 v115, v210, 16, 1
	v_bfe_u32 v116, v211, 16, 1
	v_add3_u32 v210, v210, v115, s33
	v_add3_u32 v211, v211, v116, s33
	v_perm_b32 v230, v211, v210, s19
	v_bfe_u32 v115, v212, 16, 1
	v_bfe_u32 v116, v213, 16, 1
	v_add3_u32 v212, v212, v115, s33
	v_add3_u32 v213, v213, v116, s33
	v_perm_b32 v231, v213, v212, s19
	global_store_dwordx4 v112, v[216:219], s[22:23] offset:0
	global_store_dwordx4 v112, v[220:223], s[22:23] offset:16
	global_store_dwordx4 v112, v[224:227], s[22:23] offset:32
	global_store_dwordx4 v112, v[228:231], s[22:23] offset:48
	s_barrier
	s_add_u32 s20, s20, s11
	s_add_u32 s21, s21, s11
.Lcv_loop:
	s_cmp_ge_u32 s20, s12
	s_cbranch_scc1 .Lcv_done
	s_waitcnt vmcnt(28)
	ds_write_b128 v96, v[0:3] offset:0
	ds_write_b128 v96, v[4:7] offset:4224
	ds_write_b128 v96, v[8:11] offset:8448
	ds_write_b128 v96, v[12:15] offset:12672
	ds_write_b128 v96, v[16:19] offset:16896
	ds_write_b128 v96, v[20:23] offset:21120
	ds_write_b128 v96, v[24:27] offset:25344
	ds_write_b128 v96, v[28:31] offset:29568
	s_waitcnt lgkmcnt(0)
	s_barrier
	s_cmp_lt_u32 s21, s12
	s_cselect_b32 s13, s21, s20
	s_cselect_b32 vcc_hi, 1, 0
	s_mov_b32 s28, s13
	s_cmp_lt_u32 s28, s15
	s_cbranch_scc0 .Lcv_m1_23
	s_add_u32 s29, s14, s28
	s_branch .Lcv_m3_23

.Lcv_plain_22:
	v_mul_lo_u32 v112, v113, s30
	v_add_u32_e32 v112, v112, v102
	ds_read_b32 v182, v97 offset:0
	ds_read_b32 v183, v97 offset:528
	ds_read_b32 v184, v97 offset:1056
	ds_read_b32 v185, v97 offset:1584
	ds_read_b32 v186, v97 offset:2112
	ds_read_b32 v187, v97 offset:2640
	ds_read_b32 v188, v97 offset:3168
	ds_read_b32 v189, v97 offset:3696
	ds_read_b32 v190, v97 offset:4224
	ds_read_b32 v191, v97 offset:4752
	ds_read_b32 v192, v97 offset:5280
	ds_read_b32 v193, v97 offset:5808
	ds_read_b32 v194, v97 offset:6336
	ds_read_b32 v195, v97 offset:6864
	ds_read_b32 v196, v97 offset:7392
	ds_read_b32 v197, v97 offset:7920
	ds_read_b32 v198, v97 offset:8448
	ds_read_b32 v199, v97 offset:8976
	ds_read_b32 v200, v97 offset:9504
	ds_read_b32 v201, v97 offset:10032
	ds_read_b32 v202, v97 offset:10560
	ds_read_b32 v203, v97 offset:11088
	ds_read_b32 v204, v97 offset:11616
	ds_read_b32 v205, v97 offset:12144
	ds_read_b32 v206, v97 offset:12672
	ds_read_b32 v207, v97 offset:13200
	ds_read_b32 v208, v97 offset:13728
	ds_read_b32 v209, v97 offset:14256
	ds_read_b32 v210, v97 offset:14784
	ds_read_b32 v211, v97 offset:15312
	ds_read_b32 v212, v97 offset:15840
	ds_read_b32 v213, v97 offset:16368
	s_waitcnt lgkmcnt(15)
	v_bfe_u32 v115, v182, 16, 1
	v_bfe_u32 v116, v183, 16, 1
	v_add3_u32 v182, v182, v115, s33
	v_add3_u32 v183, v183, v116, s33
	v_perm_b32 v216, v183, v182, s19
	v_bfe_u32 v115, v184, 16, 1
	v_bfe_u32 v116, v185, 16, 1
	v_add3_u32 v184, v184, v115, s33
	v_add3_u32 v185, v185, v116, s33
	v_perm_b32 v217, v185, v184, s19
	v_bfe_u32 v115, v186, 16, 1
	v_bfe_u32 v116, v187, 16, 1
	v_add3_u32 v186, v186, v115, s33
	v_add3_u32 v187, v187, v116, s33
	v_perm_b32 v218, v187, v186, s19
	v_bfe_u32 v115, v188, 16, 1
	v_bfe_u32 v116, v189, 16, 1
	v_add3_u32 v188, v188, v115, s33
	v_add3_u32 v189, v189, v116, s33
	v_perm_b32 v219, v189, v188, s19
	v_bfe_u32 v115, v190, 16, 1
	v_bfe_u32 v116, v191, 16, 1
	v_add3_u32 v190, v190, v115, s33
	v_add3_u32 v191, v191, v116, s33
	v_perm_b32 v220, v191, v190, s19
	v_bfe_u32 v115, v192, 16, 1
	v_bfe_u32 v116, v193, 16, 1
	v_add3_u32 v192, v192, v115, s33
	v_add3_u32 v193, v193, v116, s33
	v_perm_b32 v221, v193, v192, s19
	v_bfe_u32 v115, v194, 16, 1
	v_bfe_u32 v116, v195, 16, 1
	v_add3_u32 v194, v194, v115, s33
	v_add3_u32 v195, v195, v116, s33
	v_perm_b32 v222, v195, v194, s19
	v_bfe_u32 v115, v196, 16, 1
	v_bfe_u32 v116, v197, 16, 1
	v_add3_u32 v196, v196, v115, s33
	v_add3_u32 v197, v197, v116, s33
	v_perm_b32 v223, v197, v196, s19
	s_waitcnt lgkmcnt(8)
	v_bfe_u32 v115, v198, 16, 1
	v_bfe_u32 v116, v199, 16, 1
	v_add3_u32 v198, v198, v115, s33
	v_add3_u32 v199, v199, v116, s33
	v_perm_b32 v224, v199, v198, s19
	v_bfe_u32 v115, v200, 16, 1
	v_bfe_u32 v116, v201, 16, 1
	v_add3_u32 v200, v200, v115, s33
	v_add3_u32 v201, v201, v116, s33
	v_perm_b32 v225, v201, v200, s19
	v_bfe_u32 v115, v202, 16, 1
	v_bfe_u32 v116, v203, 16, 1
	v_add3_u32 v202, v202, v115, s33
	v_add3_u32 v203, v203, v116, s33
	v_perm_b32 v226, v203, v202, s19
	v_bfe_u32 v115, v204, 16, 1
	v_bfe_u32 v116, v205, 16, 1
	v_add3_u32 v204, v204, v115, s33
	v_add3_u32 v205, v205, v116, s33
	v_perm_b32 v227, v205, v204, s19
	s_waitcnt lgkmcnt(0)
	v_bfe_u32 v115, v206, 16, 1
	v_bfe_u32 v116, v207, 16, 1
	v_add3_u32 v206, v206, v115, s33
	v_add3_u32 v207, v207, v116, s33
	v_perm_b32 v228, v207, v206, s19
	v_bfe_u32 v115, v208, 16, 1
	v_bfe_u32 v116, v209, 16, 1
	v_add3_u32 v208, v208, v115, s33
	v_add3_u32 v209, v209, v116, s33
	v_perm_b32 v229, v209, v208, s19
	v_bfe_u32 v115, v210, 16, 1
	v_bfe_u32 v116, v211, 16, 1
	v_add3_u32 v210, v210, v115, s33
	v_add3_u32 v211, v211, v116, s33
	v_perm_b32 v230, v211, v210, s19
	v_bfe_u32 v115, v212, 16, 1
	v_bfe_u32 v116, v213, 16, 1
	v_add3_u32 v212, v212, v115, s33
	v_add3_u32 v213, v213, v116, s33
	v_perm_b32 v231, v213, v212, s19
	global_store_dwordx4 v112, v[216:219], s[22:23] offset:0
	global_store_dwordx4 v112, v[220:223], s[22:23] offset:16
	global_store_dwordx4 v112, v[224:227], s[22:23] offset:32
	global_store_dwordx4 v112, v[228:231], s[22:23] offset:48
	s_barrier
	s_add_u32 s20, s20, s11
	s_add_u32 s21, s21, s11
	s_cmp_ge_u32 s20, s12
	s_cbranch_scc1 .Lcv_done
	s_waitcnt vmcnt(28)
	ds_write_b128 v96, v[32:35] offset:0
	ds_write_b128 v96, v[36:39] offset:4224
	ds_write_b128 v96, v[40:43] offset:8448
	ds_write_b128 v96, v[44:47] offset:12672
	ds_write_b128 v96, v[48:51] offset:16896
	ds_write_b128 v96, v[52:55] offset:21120
	ds_write_b128 v96, v[56:59] offset:25344
	ds_write_b128 v96, v[60:63] offset:29568
	s_waitcnt lgkmcnt(0)
	s_barrier
	s_cmp_lt_u32 s21, s12
	s_cselect_b32 s13, s21, s20
	s_cselect_b32 vcc_hi, 1, 0
	s_mov_b32 s28, s13
	s_cmp_lt_u32 s28, s15
	s_cbranch_scc0 .Lcv_m1_28
	s_add_u32 s29, s14, s28
	s_branch .Lcv_m3_28

.Lcv_plain_27:
	v_mul_lo_u32 v112, v113, s30
	v_add_u32_e32 v112, v112, v102
	ds_read_b32 v182, v97 offset:0
	ds_read_b32 v183, v97 offset:528
	ds_read_b32 v184, v97 offset:1056
	ds_read_b32 v185, v97 offset:1584
	ds_read_b32 v186, v97 offset:2112
	ds_read_b32 v187, v97 offset:2640
	ds_read_b32 v188, v97 offset:3168
	ds_read_b32 v189, v97 offset:3696
	ds_read_b32 v190, v97 offset:4224
	ds_read_b32 v191, v97 offset:4752
	ds_read_b32 v192, v97 offset:5280
	ds_read_b32 v193, v97 offset:5808
	ds_read_b32 v194, v97 offset:6336
	ds_read_b32 v195, v97 offset:6864
	ds_read_b32 v196, v97 offset:7392
	ds_read_b32 v197, v97 offset:7920
	ds_read_b32 v198, v97 offset:8448
	ds_read_b32 v199, v97 offset:8976
	ds_read_b32 v200, v97 offset:9504
	ds_read_b32 v201, v97 offset:10032
	ds_read_b32 v202, v97 offset:10560
	ds_read_b32 v203, v97 offset:11088
	ds_read_b32 v204, v97 offset:11616
	ds_read_b32 v205, v97 offset:12144
	ds_read_b32 v206, v97 offset:12672
	ds_read_b32 v207, v97 offset:13200
	ds_read_b32 v208, v97 offset:13728
	ds_read_b32 v209, v97 offset:14256
	ds_read_b32 v210, v97 offset:14784
	ds_read_b32 v211, v97 offset:15312
	ds_read_b32 v212, v97 offset:15840
	ds_read_b32 v213, v97 offset:16368
	s_waitcnt lgkmcnt(15)
	v_bfe_u32 v115, v182, 16, 1
	v_bfe_u32 v116, v183, 16, 1
	v_add3_u32 v182, v182, v115, s33
	v_add3_u32 v183, v183, v116, s33
	v_perm_b32 v216, v183, v182, s19
	v_bfe_u32 v115, v184, 16, 1
	v_bfe_u32 v116, v185, 16, 1
	v_add3_u32 v184, v184, v115, s33
	v_add3_u32 v185, v185, v116, s33
	v_perm_b32 v217, v185, v184, s19
	v_bfe_u32 v115, v186, 16, 1
	v_bfe_u32 v116, v187, 16, 1
	v_add3_u32 v186, v186, v115, s33
	v_add3_u32 v187, v187, v116, s33
	v_perm_b32 v218, v187, v186, s19
	v_bfe_u32 v115, v188, 16, 1
	v_bfe_u32 v116, v189, 16, 1
	v_add3_u32 v188, v188, v115, s33
	v_add3_u32 v189, v189, v116, s33
	v_perm_b32 v219, v189, v188, s19
	v_bfe_u32 v115, v190, 16, 1
	v_bfe_u32 v116, v191, 16, 1
	v_add3_u32 v190, v190, v115, s33
	v_add3_u32 v191, v191, v116, s33
	v_perm_b32 v220, v191, v190, s19
	v_bfe_u32 v115, v192, 16, 1
	v_bfe_u32 v116, v193, 16, 1
	v_add3_u32 v192, v192, v115, s33
	v_add3_u32 v193, v193, v116, s33
	v_perm_b32 v221, v193, v192, s19
	v_bfe_u32 v115, v194, 16, 1
	v_bfe_u32 v116, v195, 16, 1
	v_add3_u32 v194, v194, v115, s33
	v_add3_u32 v195, v195, v116, s33
	v_perm_b32 v222, v195, v194, s19
	v_bfe_u32 v115, v196, 16, 1
	v_bfe_u32 v116, v197, 16, 1
	v_add3_u32 v196, v196, v115, s33
	v_add3_u32 v197, v197, v116, s33
	v_perm_b32 v223, v197, v196, s19
	s_waitcnt lgkmcnt(8)
	v_bfe_u32 v115, v198, 16, 1
	v_bfe_u32 v116, v199, 16, 1
	v_add3_u32 v198, v198, v115, s33
	v_add3_u32 v199, v199, v116, s33
	v_perm_b32 v224, v199, v198, s19
	v_bfe_u32 v115, v200, 16, 1
	v_bfe_u32 v116, v201, 16, 1
	v_add3_u32 v200, v200, v115, s33
	v_add3_u32 v201, v201, v116, s33
	v_perm_b32 v225, v201, v200, s19
	v_bfe_u32 v115, v202, 16, 1
	v_bfe_u32 v116, v203, 16, 1
	v_add3_u32 v202, v202, v115, s33
	v_add3_u32 v203, v203, v116, s33
	v_perm_b32 v226, v203, v202, s19
	v_bfe_u32 v115, v204, 16, 1
	v_bfe_u32 v116, v205, 16, 1
	v_add3_u32 v204, v204, v115, s33
	v_add3_u32 v205, v205, v116, s33
	v_perm_b32 v227, v205, v204, s19
	s_waitcnt lgkmcnt(0)
	v_bfe_u32 v115, v206, 16, 1
	v_bfe_u32 v116, v207, 16, 1
	v_add3_u32 v206, v206, v115, s33
	v_add3_u32 v207, v207, v116, s33
	v_perm_b32 v228, v207, v206, s19
	v_bfe_u32 v115, v208, 16, 1
	v_bfe_u32 v116, v209, 16, 1
	v_add3_u32 v208, v208, v115, s33
	v_add3_u32 v209, v209, v116, s33
	v_perm_b32 v229, v209, v208, s19
	v_bfe_u32 v115, v210, 16, 1
	v_bfe_u32 v116, v211, 16, 1
	v_add3_u32 v210, v210, v115, s33
	v_add3_u32 v211, v211, v116, s33
	v_perm_b32 v230, v211, v210, s19
	v_bfe_u32 v115, v212, 16, 1
	v_bfe_u32 v116, v213, 16, 1
	v_add3_u32 v212, v212, v115, s33
	v_add3_u32 v213, v213, v116, s33
	v_perm_b32 v231, v213, v212, s19
	global_store_dwordx4 v112, v[216:219], s[22:23] offset:0
	global_store_dwordx4 v112, v[220:223], s[22:23] offset:16
	global_store_dwordx4 v112, v[224:227], s[22:23] offset:32
	global_store_dwordx4 v112, v[228:231], s[22:23] offset:48
	s_barrier
	s_add_u32 s20, s20, s11
	s_add_u32 s21, s21, s11
	s_cmp_ge_u32 s20, s12
	s_cbranch_scc1 .Lcv_done
	s_waitcnt vmcnt(28)
	ds_write_b128 v96, v[64:67] offset:0
	ds_write_b128 v96, v[68:71] offset:4224
	ds_write_b128 v96, v[72:75] offset:8448
	ds_write_b128 v96, v[76:79] offset:12672
	ds_write_b128 v96, v[80:83] offset:16896
	ds_write_b128 v96, v[84:87] offset:21120
	ds_write_b128 v96, v[88:91] offset:25344
	ds_write_b128 v96, v[92:95] offset:29568
	s_waitcnt lgkmcnt(0)
	s_barrier
	s_cmp_lt_u32 s21, s12
	s_cselect_b32 s13, s21, s20
	s_cselect_b32 vcc_hi, 1, 0
	s_mov_b32 s28, s13
	s_cmp_lt_u32 s28, s15
	s_cbranch_scc0 .Lcv_m1_33
	s_add_u32 s29, s14, s28
	s_branch .Lcv_m3_33

.Lcv_plain_32:
	v_mul_lo_u32 v112, v113, s30
	v_add_u32_e32 v112, v112, v102
	ds_read_b32 v182, v97 offset:0
	ds_read_b32 v183, v97 offset:528
	ds_read_b32 v184, v97 offset:1056
	ds_read_b32 v185, v97 offset:1584
	ds_read_b32 v186, v97 offset:2112
	ds_read_b32 v187, v97 offset:2640
	ds_read_b32 v188, v97 offset:3168
	ds_read_b32 v189, v97 offset:3696
	ds_read_b32 v190, v97 offset:4224
	ds_read_b32 v191, v97 offset:4752
	ds_read_b32 v192, v97 offset:5280
	ds_read_b32 v193, v97 offset:5808
	ds_read_b32 v194, v97 offset:6336
	ds_read_b32 v195, v97 offset:6864
	ds_read_b32 v196, v97 offset:7392
	ds_read_b32 v197, v97 offset:7920
	ds_read_b32 v198, v97 offset:8448
	ds_read_b32 v199, v97 offset:8976
	ds_read_b32 v200, v97 offset:9504
	ds_read_b32 v201, v97 offset:10032
	ds_read_b32 v202, v97 offset:10560
	ds_read_b32 v203, v97 offset:11088
	ds_read_b32 v204, v97 offset:11616
	ds_read_b32 v205, v97 offset:12144
	ds_read_b32 v206, v97 offset:12672
	ds_read_b32 v207, v97 offset:13200
	ds_read_b32 v208, v97 offset:13728
	ds_read_b32 v209, v97 offset:14256
	ds_read_b32 v210, v97 offset:14784
	ds_read_b32 v211, v97 offset:15312
	ds_read_b32 v212, v97 offset:15840
	ds_read_b32 v213, v97 offset:16368
	s_waitcnt lgkmcnt(15)
	v_bfe_u32 v115, v182, 16, 1
	v_bfe_u32 v116, v183, 16, 1
	v_add3_u32 v182, v182, v115, s33
	v_add3_u32 v183, v183, v116, s33
	v_perm_b32 v216, v183, v182, s19
	v_bfe_u32 v115, v184, 16, 1
	v_bfe_u32 v116, v185, 16, 1
	v_add3_u32 v184, v184, v115, s33
	v_add3_u32 v185, v185, v116, s33
	v_perm_b32 v217, v185, v184, s19
	v_bfe_u32 v115, v186, 16, 1
	v_bfe_u32 v116, v187, 16, 1
	v_add3_u32 v186, v186, v115, s33
	v_add3_u32 v187, v187, v116, s33
	v_perm_b32 v218, v187, v186, s19
	v_bfe_u32 v115, v188, 16, 1
	v_bfe_u32 v116, v189, 16, 1
	v_add3_u32 v188, v188, v115, s33
	v_add3_u32 v189, v189, v116, s33
	v_perm_b32 v219, v189, v188, s19
	v_bfe_u32 v115, v190, 16, 1
	v_bfe_u32 v116, v191, 16, 1
	v_add3_u32 v190, v190, v115, s33
	v_add3_u32 v191, v191, v116, s33
	v_perm_b32 v220, v191, v190, s19
	v_bfe_u32 v115, v192, 16, 1
	v_bfe_u32 v116, v193, 16, 1
	v_add3_u32 v192, v192, v115, s33
	v_add3_u32 v193, v193, v116, s33
	v_perm_b32 v221, v193, v192, s19
	v_bfe_u32 v115, v194, 16, 1
	v_bfe_u32 v116, v195, 16, 1
	v_add3_u32 v194, v194, v115, s33
	v_add3_u32 v195, v195, v116, s33
	v_perm_b32 v222, v195, v194, s19
	v_bfe_u32 v115, v196, 16, 1
	v_bfe_u32 v116, v197, 16, 1
	v_add3_u32 v196, v196, v115, s33
	v_add3_u32 v197, v197, v116, s33
	v_perm_b32 v223, v197, v196, s19
	s_waitcnt lgkmcnt(8)
	v_bfe_u32 v115, v198, 16, 1
	v_bfe_u32 v116, v199, 16, 1
	v_add3_u32 v198, v198, v115, s33
	v_add3_u32 v199, v199, v116, s33
	v_perm_b32 v224, v199, v198, s19
	v_bfe_u32 v115, v200, 16, 1
	v_bfe_u32 v116, v201, 16, 1
	v_add3_u32 v200, v200, v115, s33
	v_add3_u32 v201, v201, v116, s33
	v_perm_b32 v225, v201, v200, s19
	v_bfe_u32 v115, v202, 16, 1
	v_bfe_u32 v116, v203, 16, 1
	v_add3_u32 v202, v202, v115, s33
	v_add3_u32 v203, v203, v116, s33
	v_perm_b32 v226, v203, v202, s19
	v_bfe_u32 v115, v204, 16, 1
	v_bfe_u32 v116, v205, 16, 1
	v_add3_u32 v204, v204, v115, s33
	v_add3_u32 v205, v205, v116, s33
	v_perm_b32 v227, v205, v204, s19
	s_waitcnt lgkmcnt(0)
	v_bfe_u32 v115, v206, 16, 1
	v_bfe_u32 v116, v207, 16, 1
	v_add3_u32 v206, v206, v115, s33
	v_add3_u32 v207, v207, v116, s33
	v_perm_b32 v228, v207, v206, s19
	v_bfe_u32 v115, v208, 16, 1
	v_bfe_u32 v116, v209, 16, 1
	v_add3_u32 v208, v208, v115, s33
	v_add3_u32 v209, v209, v116, s33
	v_perm_b32 v229, v209, v208, s19
	v_bfe_u32 v115, v210, 16, 1
	v_bfe_u32 v116, v211, 16, 1
	v_add3_u32 v210, v210, v115, s33
	v_add3_u32 v211, v211, v116, s33
	v_perm_b32 v230, v211, v210, s19
	v_bfe_u32 v115, v212, 16, 1
	v_bfe_u32 v116, v213, 16, 1
	v_add3_u32 v212, v212, v115, s33
	v_add3_u32 v213, v213, v116, s33
	v_perm_b32 v231, v213, v212, s19
	global_store_dwordx4 v112, v[216:219], s[22:23] offset:0
	global_store_dwordx4 v112, v[220:223], s[22:23] offset:16
	global_store_dwordx4 v112, v[224:227], s[22:23] offset:32
	global_store_dwordx4 v112, v[228:231], s[22:23] offset:48
	s_barrier
	s_add_u32 s20, s20, s11
	s_add_u32 s21, s21, s11
	s_branch .Lcv_loop
.Lcv_single:
	s_waitcnt lgkmcnt(0)
	s_mov_b32 vcc_hi, 1
	s_mov_b32 s28, s20
	s_cmp_lt_u32 s28, s15
	s_cbranch_scc0 .Lcv_m1_37
	s_add_u32 s29, s14, s28
	s_branch .Lcv_m3_37

.Lcv_dZ_38:
	s_load_dwordx2 s[22:23], s[4:5], s101
	s_mul_i32 s24, s24, vcc_hi
	s_mul_i32 s31, s25, s24
	s_lshl_b32 s28, s26, 2
	s_add_u32 s31, s31, s28
	s_add_u32 s31, s31, s98
	s_lshl_b32 s28, s24, 3
	v_mad_u32_u24 v104, v100, s24, v101
	v_add_u32_e32 v105, s28, v104
	v_add_u32_e32 v106, s28, v105
	v_add_u32_e32 v107, s28, v106
	v_add_u32_e32 v108, s28, v107
	v_add_u32_e32 v109, s28, v108
	v_add_u32_e32 v110, s28, v109
	v_add_u32_e32 v111, s28, v110
	s_waitcnt lgkmcnt(0)
	s_add_u32 s22, s22, s31
	s_addc_u32 s23, s23, 0
	global_load_dwordx4 v[0:3], v104, s[22:23] nt
	global_load_dwordx4 v[4:7], v105, s[22:23] nt
	global_load_dwordx4 v[8:11], v106, s[22:23] nt
	global_load_dwordx4 v[12:15], v107, s[22:23] nt
	global_load_dwordx4 v[16:19], v108, s[22:23] nt
	global_load_dwordx4 v[20:23], v109, s[22:23] nt
	global_load_dwordx4 v[24:27], v110, s[22:23] nt
	global_load_dwordx4 v[28:31], v111, s[22:23] nt
	s_waitcnt vmcnt(0)
	ds_write_b128 v96, v[0:3] offset:0
	ds_write_b128 v96, v[4:7] offset:4224
	ds_write_b128 v96, v[8:11] offset:8448
	ds_write_b128 v96, v[12:15] offset:12672
	ds_write_b128 v96, v[16:19] offset:16896
	ds_write_b128 v96, v[20:23] offset:21120
	ds_write_b128 v96, v[24:27] offset:25344
	ds_write_b128 v96, v[28:31] offset:29568
	s_waitcnt lgkmcnt(0)
	s_barrier
	s_mov_b32 s28, s20
	s_cmp_lt_u32 s28, s15
	s_cbranch_scc0 .Lcv_m1_40
	s_add_u32 s29, s14, s28
	s_branch .Lcv_m3_40

.Lcv_done:
	s_waitcnt vmcnt(0) lgkmcnt(0)
.Lcv_exit:
	s_waitcnt lgkmcnt(0)
	v_readlane_b32 s4, v238, 33
	v_readlane_b32 s5, v238, 34
	v_readlane_b32 s6, v238, 35
	v_readlane_b32 s7, v238, 36
	v_readlane_b32 s8, v238, 37
	v_readlane_b32 s9, v238, 38
	v_readlane_b32 s10, v238, 39
	v_readlane_b32 s11, v238, 40
	v_readlane_b32 s12, v238, 41
	v_readlane_b32 s13, v238, 42
	v_readlane_b32 s14, v238, 43
	v_readlane_b32 s15, v238, 44
	v_readlane_b32 s16, v238, 45
	v_readlane_b32 s17, v238, 46
	v_readlane_b32 s18, v238, 47
	v_readlane_b32 s19, v238, 48
	v_readlane_b32 s20, v238, 49
	v_readlane_b32 s21, v238, 50
	v_readlane_b32 s22, v238, 51
	v_readlane_b32 s23, v238, 52
	v_readlane_b32 s24, v238, 53
	v_readlane_b32 s25, v238, 54
	v_readlane_b32 s26, v238, 55
	v_readlane_b32 s27, v238, 56
	v_readlane_b32 s28, v238, 57
	v_readlane_b32 s29, v238, 58
	v_readlane_b32 s30, v238, 59
	v_readlane_b32 s31, v238, 60
	s_nop 4
	s_cmp_eq_u32 s100, 5
	s_cbranch_scc1 .Lcv_ret_inp
	s_cmp_eq_u32 s100, 10
	s_cbranch_scc1 .Lcv_ret_gu2
	s_cmp_eq_u32 s100, 20
	s_cbranch_scc1 .Lcv_ret_gu2
	s_branch .Lcv_ret_gu1

.Lcv_ret_inp:
.LBB0_1109:
	s_mov_b64 s[8:9], 0

.Lcv_ret_gu1:
.LBB0_1388:
	v_readlane_b32 s4, v238, 1
	v_readlane_b32 s5, v238, 2
	s_mov_b64 s[0:1], 0
	s_and_b64 vcc, exec, s[4:5]
	s_cbranch_vccz .LBB0_1390
	v_readlane_b32 s4, v238, 3
	s_cmp_gt_i32 s4, 0
	s_mov_b64 s[0:1], -1
	s_cselect_b64 s[8:9], -1, 0

.Lpost_getpc0:
	s_add_u32 s98, s98, (.LBB0_7-.Lpost_getpc0)&4294967295
	s_addc_u32 s99, s99, (.LBB0_7-.Lpost_getpc0)>>32
	s_setpc_b64 s[98:99]
.LBB0_1526:
	v_readlane_b32 s4, v242, 51
	s_mov_b64 s[8:9], 0x200
	s_movk_i32 s5, 0x100
	s_waitcnt lgkmcnt(0)
	s_mov_b32 s6, s4
	v_readlane_b32 s4, v242, 50
